# grid barrier: two release polls kept in flight half a round trip apart, no drain of the last poll
# baseline (speedup 1.0000x reference)
; __device__ __forceinline__ unsigned xb_ld(unsigned* p)              { return __hip_atomic_load(p, __ATOMIC_RELAXED, __HIP_MEMORY_SCOPE_AGENT); }
; __device__ __forceinline__ unsigned xb_add(unsigned* p, unsigned v) { return __hip_atomic_fetch_add(p, v, __ATOMIC_RELAXED, __HIP_MEMORY_SCOPE_AGENT); }
; #define XB_SPIN(cond, bar) do { unsigned _sp = 0; while (cond) { __builtin_amdgcn_s_sleep(1); \
;     if ((++_sp & 255u) == 0u) { if (xb_ld(&(bar)[XB_TMO])) break; if (_sp > XB_SPIN_CAP) { atomicAdd(&(bar)[XB_TMO], 1u); break; } } } } while (0)
; __device__ __forceinline__ void xcd_barrier(const XcdBarrier& b) {
;     ...
;             else XB_SPIN(xb_ld(&bar[XB_TOPGEN]) == tg, bar);
;             __builtin_amdgcn_fence(__ATOMIC_ACQUIRE, "agent");
;             xb_add(&bar[XB_XGEN(b.x)], 1u);
;             asm volatile("s_waitcnt vmcnt(0)" ::: "memory");
;         } else {
;             XB_SPIN(xb_ld(&bar[XB_XGEN(b.x)]) == gen, bar);
;             __builtin_amdgcn_fence(__ATOMIC_ACQUIRE, "agent");
;             asm volatile("s_waitcnt vmcnt(0)" ::: "memory");
.Lxb0_poll:
	global_load_dword v252, v5, s[2:3] sc1
	s_sleep 9
.Lxb0_pl:
	global_load_dword v253, v5, s[2:3] sc1
	s_waitcnt vmcnt(1)
	v_cmp_lt_u32_e32 vcc, v252, v7
	s_cbranch_vccz .Lxb0_done
	global_load_dword v252, v5, s[2:3] sc1
	s_waitcnt vmcnt(1)
	v_cmp_lt_u32_e32 vcc, v253, v7
	s_cbranch_vccz .Lxb0_done
	s_add_i32 s98, s98, 1
	s_cmp_lt_u32 s98, 0x40000
	s_cbranch_scc1 .Lxb0_pl
.Lxb0_done:
	s_nop 0
	s_nop 0

; __device__ __forceinline__ unsigned xb_ld(unsigned* p)              { return __hip_atomic_load(p, __ATOMIC_RELAXED, __HIP_MEMORY_SCOPE_AGENT); }
; #define XB_SPIN(cond, bar) do { unsigned _sp = 0; while (cond) { __builtin_amdgcn_s_sleep(1); \
;     if ((++_sp & 255u) == 0u) { if (xb_ld(&(bar)[XB_TMO])) break; if (_sp > XB_SPIN_CAP) { atomicAdd(&(bar)[XB_TMO], 1u); break; } } } } while (0)
; __device__ __forceinline__ void xcd_barrier(const XcdBarrier& b) {
;     ...
;             asm volatile("s_waitcnt vmcnt(0)" ::: "memory");
;         } else {
;             XB_SPIN(xb_ld(&bar[XB_XGEN(b.x)]) == gen, bar);
;             __builtin_amdgcn_fence(__ATOMIC_ACQUIRE, "agent");
;             asm volatile("s_waitcnt vmcnt(0)" ::: "memory");
.Lxb10_done:
	s_nop 0
	s_nop 0
	s_mov_b64 s[12:13], exec
	s_getpc_b64 s[98:99]
